# rw_finish: nontemporal hint on its one-time operand reads
# baseline (speedup 1.0000x reference)
.LBB0_166:
	s_ashr_i32 s4, s40, 3
	s_mov_b32 s7, s73
	s_mov_b32 s6, 0x3a27c5ac
	s_ashr_i32 s5, s4, 31
	v_mov_b64_e32 v[4:5], s[6:7]
	s_mul_hi_i32 s6, s4, 0xc00
	s_mul_i32 s8, s4, 0xc00
	s_lshl_b64 s[4:5], s[4:5], 9
	v_lshl_add_u64 v[36:37], s[4:5], 0, v[2:3]
	s_add_u32 s4, s12, s8
	s_addc_u32 s5, s13, s6
	s_and_b32 s72, s29, 0x100
	s_mov_b32 s9, s73
	s_mov_b32 s37, s73
	s_mov_b32 s39, s73
	s_or_b32 s8, s72, 64
	s_or_b32 s36, s72, 0x80
	s_or_b32 s38, s72, 0xc0
	v_add_u32_e32 v44, s72, v2
	v_lshl_add_u64 v[40:41], v[2:3], 1, s[4:5]
	v_lshl_add_u64 v[42:43], v[36:37], 0, s[72:73]
	s_lshl_b32 s6, s72, 1
	v_lshl_add_u64 v[46:47], v[36:37], 0, s[8:9]
	v_lshl_add_u64 v[48:49], v[36:37], 0, s[36:37]
	v_lshl_add_u64 v[50:51], v[36:37], 0, s[38:39]
	v_ashrrev_i32_e32 v45, 31, v44
	v_lshl_add_u64 v[40:41], v[40:41], 0, s[6:7]
	v_lshlrev_b64 v[42:43], 1, v[42:43]
	s_mov_b64 s[4:5], 0xe8c0800
	v_lshlrev_b64 v[46:47], 1, v[46:47]
	v_lshlrev_b64 v[48:49], 1, v[48:49]
	v_lshlrev_b64 v[50:51], 1, v[50:51]
	v_lshlrev_b64 v[44:45], 2, v[44:45]
	v_lshl_add_u64 v[36:37], v[40:41], 0, s[4:5]
	v_lshl_add_u64 v[52:53], s[14:15], 0, v[42:43]
	v_lshl_add_u64 v[42:43], s[20:21], 0, v[42:43]
	v_add_co_u32_e32 v40, vcc, s81, v40
	v_lshl_add_u64 v[54:55], s[14:15], 0, v[46:47]
	v_lshl_add_u64 v[46:47], s[20:21], 0, v[46:47]
	v_lshl_add_u64 v[56:57], s[14:15], 0, v[48:49]
	v_lshl_add_u64 v[48:49], s[20:21], 0, v[48:49]
	v_lshl_add_u64 v[58:59], s[14:15], 0, v[50:51]
	v_lshl_add_u64 v[50:51], s[20:21], 0, v[50:51]
	v_lshl_add_u64 v[60:61], s[30:31], 0, v[44:45]
	v_addc_co_u32_e32 v41, vcc, 0, v41, vcc
	v_lshl_add_u64 v[44:45], s[34:35], 0, v[44:45]
	global_load_ushort v0, v[52:53], off nt
	s_nop 0
	global_load_ushort v42, v[42:43], off nt
	s_nop 0
	global_load_ushort v43, v[36:37], off offset:128 nt
	global_load_ushort v52, v[36:37], off offset:256 nt
	global_load_ushort v53, v[36:37], off offset:384 nt
	s_nop 0
	global_load_ushort v54, v[54:55], off nt
	s_nop 0
	global_load_ushort v46, v[46:47], off nt
	s_nop 0
	global_load_ushort v47, v[40:41], off offset:2048 nt
	global_load_ushort v55, v[56:57], off nt
	s_nop 0
	global_load_ushort v48, v[48:49], off nt
	s_nop 0
	global_load_ushort v49, v[58:59], off nt
	s_nop 0
	global_load_ushort v50, v[50:51], off nt
	s_nop 0
	global_load_dword v51, v[60:61], off
	global_load_dword v56, v[60:61], off offset:256
	global_load_dword v57, v[60:61], off offset:512
	global_load_dword v58, v[60:61], off offset:768
	global_load_dword v59, v[44:45], off
	s_nop 0
	global_load_dword v60, v[44:45], off offset:256
	global_load_dword v61, v[44:45], off offset:512
	global_load_dword v62, v[44:45], off offset:768
	s_add_i32 s40, s40, s41
	s_add_i32 s29, s29, s80
	s_cmp_lt_i32 s40, 0x21000
	s_cselect_b32 s98, 1, 0
	global_load_ushort v128, v[36:37], off offset:128
	global_load_ushort v128, v[36:37], off offset:128
	global_load_ushort v128, v[36:37], off offset:128
	global_load_ushort v128, v[36:37], off offset:128
.Lrwf_loop:
	s_cmp_eq_u32 s98, 0
	s_cbranch_scc1 .Lrwf_tail1
	s_ashr_i32 s4, s40, 3
	s_mov_b32 s7, s73
	s_mov_b32 s6, 0x3a27c5ac
	s_ashr_i32 s5, s4, 31
	v_mov_b64_e32 v[68:69], s[6:7]
	s_mul_hi_i32 s6, s4, 0xc00
	s_mul_i32 s8, s4, 0xc00
	s_lshl_b64 s[4:5], s[4:5], 9
	v_lshl_add_u64 v[100:101], s[4:5], 0, v[2:3]
	s_add_u32 s4, s12, s8
	s_addc_u32 s5, s13, s6
	s_and_b32 s72, s29, 0x100
	s_mov_b32 s9, s73
	s_mov_b32 s37, s73
	s_mov_b32 s39, s73
	s_or_b32 s8, s72, 64
	s_or_b32 s36, s72, 0x80
	s_or_b32 s38, s72, 0xc0
	v_add_u32_e32 v108, s72, v2
	v_lshl_add_u64 v[104:105], v[2:3], 1, s[4:5]
	v_lshl_add_u64 v[106:107], v[100:101], 0, s[72:73]
	s_lshl_b32 s6, s72, 1
	v_lshl_add_u64 v[110:111], v[100:101], 0, s[8:9]
	v_lshl_add_u64 v[112:113], v[100:101], 0, s[36:37]
	v_lshl_add_u64 v[114:115], v[100:101], 0, s[38:39]
	v_ashrrev_i32_e32 v109, 31, v108
	v_lshl_add_u64 v[104:105], v[104:105], 0, s[6:7]
	v_lshlrev_b64 v[106:107], 1, v[106:107]
	s_mov_b64 s[4:5], 0xe8c0800
	v_lshlrev_b64 v[110:111], 1, v[110:111]
	v_lshlrev_b64 v[112:113], 1, v[112:113]
	v_lshlrev_b64 v[114:115], 1, v[114:115]
	v_lshlrev_b64 v[108:109], 2, v[108:109]
	v_lshl_add_u64 v[100:101], v[104:105], 0, s[4:5]
	v_lshl_add_u64 v[116:117], s[14:15], 0, v[106:107]
	v_lshl_add_u64 v[106:107], s[20:21], 0, v[106:107]
	v_add_co_u32_e32 v104, vcc, s81, v104
	v_lshl_add_u64 v[118:119], s[14:15], 0, v[110:111]
	v_lshl_add_u64 v[110:111], s[20:21], 0, v[110:111]
	v_lshl_add_u64 v[120:121], s[14:15], 0, v[112:113]
	v_lshl_add_u64 v[112:113], s[20:21], 0, v[112:113]
	v_lshl_add_u64 v[122:123], s[14:15], 0, v[114:115]
	v_lshl_add_u64 v[114:115], s[20:21], 0, v[114:115]
	v_lshl_add_u64 v[124:125], s[30:31], 0, v[108:109]
	v_addc_co_u32_e32 v105, vcc, 0, v105, vcc
	v_lshl_add_u64 v[108:109], s[34:35], 0, v[108:109]
	global_load_ushort v64, v[116:117], off nt
	s_nop 0
	global_load_ushort v106, v[106:107], off nt
	s_nop 0
	global_load_ushort v107, v[100:101], off offset:128 nt
	global_load_ushort v116, v[100:101], off offset:256 nt
	global_load_ushort v117, v[100:101], off offset:384 nt
	s_nop 0
	global_load_ushort v118, v[118:119], off nt
	s_nop 0
	global_load_ushort v110, v[110:111], off nt
	s_nop 0
	global_load_ushort v111, v[104:105], off offset:2048 nt
	global_load_ushort v119, v[120:121], off nt
	s_nop 0
	global_load_ushort v112, v[112:113], off nt
	s_nop 0
	global_load_ushort v113, v[122:123], off nt
	s_nop 0
	global_load_ushort v114, v[114:115], off nt
	s_nop 0
	global_load_dword v115, v[124:125], off
	global_load_dword v120, v[124:125], off offset:256
	global_load_dword v121, v[124:125], off offset:512
	global_load_dword v122, v[124:125], off offset:768
	global_load_dword v123, v[108:109], off
	s_nop 0
	global_load_dword v124, v[108:109], off offset:256
	global_load_dword v125, v[108:109], off offset:512
	global_load_dword v126, v[108:109], off offset:768
	s_add_i32 s40, s40, s41
	s_add_i32 s29, s29, s80
	s_cmp_lt_i32 s40, 0x21000
	s_cselect_b32 s98, 1, 0
	v_mov_b32_e32 v35, v1
	v_mov_b32_e32 v34, v1
	v_mov_b32_e32 v15, v1
	v_mov_b32_e32 v14, v1
	v_mov_b32_e32 v39, v1
	v_mov_b32_e32 v38, v1
	v_mov_b32_e32 v21, v1
	v_mov_b32_e32 v20, v1
	v_mov_b32_e32 v33, v1
	v_mov_b32_e32 v32, v1
	v_mov_b32_e32 v19, v1
	v_mov_b32_e32 v18, v1
	v_mov_b32_e32 v31, v1
	v_mov_b32_e32 v30, v1
	v_mov_b32_e32 v17, v1
	v_mov_b32_e32 v16, v1
	v_mov_b32_e32 v29, v1
	v_mov_b32_e32 v28, v1
	v_mov_b32_e32 v13, v1
	v_mov_b32_e32 v12, v1
	v_mov_b32_e32 v27, v1
	v_mov_b32_e32 v26, v1
	v_mov_b32_e32 v11, v1
	v_mov_b32_e32 v10, v1
	v_mov_b32_e32 v25, v1
	v_mov_b32_e32 v24, v1
	v_mov_b32_e32 v9, v1
	v_mov_b32_e32 v8, v1
	v_mov_b32_e32 v23, v1
	v_mov_b32_e32 v22, v1
	v_mov_b32_e32 v7, v1
	v_mov_b32_e32 v6, v1
	s_waitcnt vmcnt(43)
	v_lshlrev_b32_e32 v0, 16, v0
	s_waitcnt vmcnt(42)
	v_lshlrev_b32_e32 v63, 16, v42
	s_waitcnt vmcnt(41)
	v_lshlrev_b32_e32 v42, 16, v43
	s_waitcnt vmcnt(40)
	v_lshlrev_b32_e32 v45, 16, v52
	s_waitcnt vmcnt(39)
	v_lshlrev_b32_e32 v44, 16, v53
	v_mov_b32_dpp v14, v42 quad_perm:[1,0,3,2] row_mask:0xf bank_mask:0xf
	v_mov_b32_dpp v35, v45 quad_perm:[1,0,3,2] row_mask:0xf bank_mask:0xf
	s_waitcnt vmcnt(36)
	v_lshlrev_b32_e32 v43, 16, v47
	v_mov_b32_dpp v34, v44 quad_perm:[1,0,3,2] row_mask:0xf bank_mask:0xf
	v_pk_add_f32 v[34:35], v[44:45], v[34:35]
	v_mov_b32_dpp v15, v43 quad_perm:[1,0,3,2] row_mask:0xf bank_mask:0xf
	v_pk_add_f32 v[14:15], v[42:43], v[14:15]
	v_mov_b32_dpp v39, v35 quad_perm:[2,3,0,1] row_mask:0xf bank_mask:0xf
	v_mov_b32_dpp v38, v34 quad_perm:[2,3,0,1] row_mask:0xf bank_mask:0xf
	v_mov_b32_dpp v21, v15 quad_perm:[2,3,0,1] row_mask:0xf bank_mask:0xf
	v_mov_b32_dpp v20, v14 quad_perm:[2,3,0,1] row_mask:0xf bank_mask:0xf
	v_pk_add_f32 v[34:35], v[34:35], v[38:39]
	v_pk_add_f32 v[14:15], v[14:15], v[20:21]
	s_waitcnt vmcnt(35)
	v_lshlrev_b32_e32 v52, 16, v55
	v_mov_b32_dpp v33, v35 row_half_mirror row_mask:0xf bank_mask:0xf
	v_mov_b32_dpp v32, v34 row_half_mirror row_mask:0xf bank_mask:0xf
	v_mov_b32_dpp v19, v15 row_half_mirror row_mask:0xf bank_mask:0xf
	v_mov_b32_dpp v18, v14 row_half_mirror row_mask:0xf bank_mask:0xf
	v_pk_add_f32 v[20:21], v[34:35], v[32:33]
	v_pk_add_f32 v[14:15], v[14:15], v[18:19]
	v_lshlrev_b32_e32 v47, 16, v54
	v_mov_b32_dpp v31, v21 row_mirror row_mask:0xf bank_mask:0xf
	v_mov_b32_dpp v30, v20 row_mirror row_mask:0xf bank_mask:0xf
	v_mov_b32_dpp v17, v15 row_mirror row_mask:0xf bank_mask:0xf
	v_mov_b32_dpp v16, v14 row_mirror row_mask:0xf bank_mask:0xf
	v_pk_add_f32 v[18:19], v[20:21], v[30:31]
	v_pk_add_f32 v[14:15], v[14:15], v[16:17]
	ds_bpermute_b32 v17, v167, v19
	ds_bpermute_b32 v16, v167, v18
	ds_bpermute_b32 v21, v167, v15
	ds_bpermute_b32 v20, v167, v14
	s_waitcnt vmcnt(34)
	v_lshlrev_b32_e32 v48, 16, v48
	s_waitcnt vmcnt(33)
	v_lshlrev_b32_e32 v49, 16, v49
	s_waitcnt lgkmcnt(2)
	v_pk_add_f32 v[16:17], v[18:19], v[16:17]
	ds_bpermute_b32 v19, v168, v17
	s_waitcnt lgkmcnt(1)
	v_pk_add_f32 v[14:15], v[14:15], v[20:21]
	ds_bpermute_b32 v18, v168, v16
	ds_bpermute_b32 v21, v168, v15
	ds_bpermute_b32 v20, v168, v14
	v_lshlrev_b32_e32 v46, 16, v46
	s_waitcnt vmcnt(32)
	v_lshlrev_b32_e32 v50, 16, v50
	s_waitcnt lgkmcnt(2)
	v_pk_add_f32 v[16:17], v[16:17], v[18:19]
	s_waitcnt lgkmcnt(0)
	v_pk_add_f32 v[14:15], v[14:15], v[20:21]
	v_pk_fma_f32 v[16:17], v[16:17], s[42:43], v[44:45] op_sel_hi:[1,0,1] neg_lo:[1,0,0] neg_hi:[1,0,0]
	v_pk_fma_f32 v[14:15], v[14:15], s[42:43], v[42:43] op_sel_hi:[1,0,1] neg_lo:[1,0,0] neg_hi:[1,0,0]
	v_pk_mul_f32 v[18:19], v[16:17], v[16:17]
	v_pk_mul_f32 v[20:21], v[14:15], v[14:15]
	s_nop 0
	v_mov_b32_dpp v29, v19 quad_perm:[1,0,3,2] row_mask:0xf bank_mask:0xf
	v_mov_b32_dpp v28, v18 quad_perm:[1,0,3,2] row_mask:0xf bank_mask:0xf
	v_mov_b32_dpp v13, v21 quad_perm:[1,0,3,2] row_mask:0xf bank_mask:0xf
	v_mov_b32_dpp v12, v20 quad_perm:[1,0,3,2] row_mask:0xf bank_mask:0xf
	v_pk_fma_f32 v[18:19], v[16:17], v[16:17], v[28:29]
	v_pk_fma_f32 v[12:13], v[14:15], v[14:15], v[12:13]
	s_nop 0
	v_mov_b32_dpp v27, v19 quad_perm:[2,3,0,1] row_mask:0xf bank_mask:0xf
	v_mov_b32_dpp v26, v18 quad_perm:[2,3,0,1] row_mask:0xf bank_mask:0xf
	v_mov_b32_dpp v11, v13 quad_perm:[2,3,0,1] row_mask:0xf bank_mask:0xf
	v_mov_b32_dpp v10, v12 quad_perm:[2,3,0,1] row_mask:0xf bank_mask:0xf
	v_pk_add_f32 v[18:19], v[18:19], v[26:27]
	v_pk_add_f32 v[10:11], v[12:13], v[10:11]
	s_nop 0
	v_mov_b32_dpp v25, v19 row_half_mirror row_mask:0xf bank_mask:0xf
	v_mov_b32_dpp v24, v18 row_half_mirror row_mask:0xf bank_mask:0xf
	v_mov_b32_dpp v9, v11 row_half_mirror row_mask:0xf bank_mask:0xf
	v_mov_b32_dpp v8, v10 row_half_mirror row_mask:0xf bank_mask:0xf
	v_pk_add_f32 v[12:13], v[18:19], v[24:25]
	v_pk_add_f32 v[8:9], v[10:11], v[8:9]
	s_nop 0
	v_mov_b32_dpp v23, v13 row_mirror row_mask:0xf bank_mask:0xf
	v_mov_b32_dpp v22, v12 row_mirror row_mask:0xf bank_mask:0xf
	v_mov_b32_dpp v7, v9 row_mirror row_mask:0xf bank_mask:0xf
	v_mov_b32_dpp v6, v8 row_mirror row_mask:0xf bank_mask:0xf
	v_pk_add_f32 v[10:11], v[12:13], v[22:23]
	v_pk_add_f32 v[6:7], v[8:9], v[6:7]
	ds_bpermute_b32 v9, v167, v11
	ds_bpermute_b32 v8, v167, v10
	ds_bpermute_b32 v13, v167, v7
	ds_bpermute_b32 v12, v167, v6
	s_waitcnt lgkmcnt(2)
	v_pk_add_f32 v[8:9], v[10:11], v[8:9]
	ds_bpermute_b32 v11, v168, v9
	s_waitcnt lgkmcnt(1)
	v_pk_add_f32 v[6:7], v[6:7], v[12:13]
	ds_bpermute_b32 v10, v168, v8
	ds_bpermute_b32 v13, v168, v7
	ds_bpermute_b32 v12, v168, v6
	s_waitcnt lgkmcnt(2)
	v_pk_add_f32 v[8:9], v[8:9], v[10:11]
	s_nop 0
	v_pk_fma_f32 v[8:9], v[8:9], s[42:43], v[4:5] op_sel_hi:[1,0,0]
	s_waitcnt lgkmcnt(0)
	v_pk_add_f32 v[6:7], v[6:7], v[12:13]
	v_cmp_gt_f32_e64 s[4:5], s74, v9
	v_pk_fma_f32 v[4:5], v[6:7], s[42:43], v[4:5] op_sel_hi:[1,0,0]
	v_mul_f32_e32 v6, 0x4b800000, v9
	v_mul_f32_e32 v7, 0x4b800000, v8
	v_cmp_gt_f32_e32 vcc, s74, v8
	v_mul_f32_e32 v10, 0x4b800000, v5
	v_mul_f32_e32 v11, 0x4b800000, v4
	v_cmp_gt_f32_e64 s[6:7], s74, v4
	v_cndmask_b32_e64 v6, v9, v6, s[4:5]
	v_cmp_gt_f32_e64 s[8:9], s74, v5
	v_cndmask_b32_e32 v7, v8, v7, vcc
	v_cndmask_b32_e64 v4, v4, v11, s[6:7]
	v_cndmask_b32_e64 v5, v5, v10, s[8:9]
	v_rsq_f32_e32 v6, v6
	v_rsq_f32_e32 v7, v7
	v_rsq_f32_e32 v5, v5
	v_rsq_f32_e32 v4, v4
	v_mul_f32_e32 v8, 0x45800000, v6
	v_mul_f32_e32 v9, 0x45800000, v7
	v_mul_f32_e32 v10, 0x45800000, v5
	v_mul_f32_e32 v11, 0x45800000, v4
	v_cndmask_b32_e64 v6, v6, v8, s[4:5]
	v_cndmask_b32_e32 v7, v7, v9, vcc
	v_cndmask_b32_e64 v5, v5, v10, s[8:9]
	v_cndmask_b32_e64 v4, v4, v11, s[6:7]
	v_mul_f32_e32 v6, v17, v6
	v_mul_f32_e32 v7, v16, v7
	v_mul_f32_e32 v5, v15, v5
	v_mul_f32_e32 v4, v14, v4
	s_waitcnt vmcnt(25)
	v_fmac_f32_e32 v61, v57, v6
	s_waitcnt vmcnt(24)
	v_fmac_f32_e32 v62, v58, v7
	v_fmac_f32_e32 v59, v51, v5
	v_fmac_f32_e32 v60, v56, v4
	v_add_f32_e32 v4, v61, v52
	v_add_f32_e32 v5, v62, v49
	v_add_f32_e32 v0, v59, v0
	v_add_f32_e32 v6, v60, v47
	v_mul_f32_e32 v4, v4, v48
	v_mul_f32_e32 v5, v5, v50
	v_mul_f32_e32 v0, v0, v63
	v_mul_f32_e32 v6, v6, v46
	v_bfe_u32 v7, v4, 16, 1
	v_bfe_u32 v8, v5, 16, 1
	v_bfe_u32 v9, v0, 16, 1
	v_bfe_u32 v10, v6, 16, 1
	v_add3_u32 v4, v4, v7, s78
	v_add3_u32 v5, v5, v8, s78
	v_add3_u32 v0, v0, v9, s78
	v_add3_u32 v6, v6, v10, s78
	global_store_short_d16_hi v[36:37], v4, off offset:256
	global_store_short_d16_hi v[36:37], v5, off offset:384
	global_store_short_d16_hi v[40:41], v0, off offset:2048
	global_store_short_d16_hi v[36:37], v6, off offset:128
	s_cmp_eq_u32 s98, 0
	s_cbranch_scc1 .Lrwf_tail2
	s_ashr_i32 s4, s40, 3
	s_mov_b32 s7, s73
	s_mov_b32 s6, 0x3a27c5ac
	s_ashr_i32 s5, s4, 31
	v_mov_b64_e32 v[4:5], s[6:7]
	s_mul_hi_i32 s6, s4, 0xc00
	s_mul_i32 s8, s4, 0xc00
	s_lshl_b64 s[4:5], s[4:5], 9
	v_lshl_add_u64 v[36:37], s[4:5], 0, v[2:3]
	s_add_u32 s4, s12, s8
	s_addc_u32 s5, s13, s6
	s_and_b32 s72, s29, 0x100
	s_mov_b32 s9, s73
	s_mov_b32 s37, s73
	s_mov_b32 s39, s73
	s_or_b32 s8, s72, 64
	s_or_b32 s36, s72, 0x80
	s_or_b32 s38, s72, 0xc0
	v_add_u32_e32 v44, s72, v2
	v_lshl_add_u64 v[40:41], v[2:3], 1, s[4:5]
	v_lshl_add_u64 v[42:43], v[36:37], 0, s[72:73]
	s_lshl_b32 s6, s72, 1
	v_lshl_add_u64 v[46:47], v[36:37], 0, s[8:9]
	v_lshl_add_u64 v[48:49], v[36:37], 0, s[36:37]
	v_lshl_add_u64 v[50:51], v[36:37], 0, s[38:39]
	v_ashrrev_i32_e32 v45, 31, v44
	v_lshl_add_u64 v[40:41], v[40:41], 0, s[6:7]
	v_lshlrev_b64 v[42:43], 1, v[42:43]
	s_mov_b64 s[4:5], 0xe8c0800
	v_lshlrev_b64 v[46:47], 1, v[46:47]
	v_lshlrev_b64 v[48:49], 1, v[48:49]
	v_lshlrev_b64 v[50:51], 1, v[50:51]
	v_lshlrev_b64 v[44:45], 2, v[44:45]
	v_lshl_add_u64 v[36:37], v[40:41], 0, s[4:5]
	v_lshl_add_u64 v[52:53], s[14:15], 0, v[42:43]
	v_lshl_add_u64 v[42:43], s[20:21], 0, v[42:43]
	v_add_co_u32_e32 v40, vcc, s81, v40
	v_lshl_add_u64 v[54:55], s[14:15], 0, v[46:47]
	v_lshl_add_u64 v[46:47], s[20:21], 0, v[46:47]
	v_lshl_add_u64 v[56:57], s[14:15], 0, v[48:49]
	v_lshl_add_u64 v[48:49], s[20:21], 0, v[48:49]
	v_lshl_add_u64 v[58:59], s[14:15], 0, v[50:51]
	v_lshl_add_u64 v[50:51], s[20:21], 0, v[50:51]
	v_lshl_add_u64 v[60:61], s[30:31], 0, v[44:45]
	v_addc_co_u32_e32 v41, vcc, 0, v41, vcc
	v_lshl_add_u64 v[44:45], s[34:35], 0, v[44:45]
	global_load_ushort v0, v[52:53], off nt
	s_nop 0
	global_load_ushort v42, v[42:43], off nt
	s_nop 0
	global_load_ushort v43, v[36:37], off offset:128 nt
	global_load_ushort v52, v[36:37], off offset:256 nt
	global_load_ushort v53, v[36:37], off offset:384 nt
	s_nop 0
	global_load_ushort v54, v[54:55], off nt
	s_nop 0
	global_load_ushort v46, v[46:47], off nt
	s_nop 0
	global_load_ushort v47, v[40:41], off offset:2048 nt
	global_load_ushort v55, v[56:57], off nt
	s_nop 0
	global_load_ushort v48, v[48:49], off nt
	s_nop 0
	global_load_ushort v49, v[58:59], off nt
	s_nop 0
	global_load_ushort v50, v[50:51], off nt
	s_nop 0
	global_load_dword v51, v[60:61], off
	global_load_dword v56, v[60:61], off offset:256
	global_load_dword v57, v[60:61], off offset:512
	global_load_dword v58, v[60:61], off offset:768
	global_load_dword v59, v[44:45], off
	s_nop 0
	global_load_dword v60, v[44:45], off offset:256
	global_load_dword v61, v[44:45], off offset:512
	global_load_dword v62, v[44:45], off offset:768
	s_add_i32 s40, s40, s41
	s_add_i32 s29, s29, s80
	s_cmp_lt_i32 s40, 0x21000
	s_cselect_b32 s98, 1, 0
	v_mov_b32_e32 v99, v1
	v_mov_b32_e32 v98, v1
	v_mov_b32_e32 v79, v1
	v_mov_b32_e32 v78, v1
	v_mov_b32_e32 v103, v1
	v_mov_b32_e32 v102, v1
	v_mov_b32_e32 v85, v1
	v_mov_b32_e32 v84, v1
	v_mov_b32_e32 v97, v1
	v_mov_b32_e32 v96, v1
	v_mov_b32_e32 v83, v1
	v_mov_b32_e32 v82, v1
	v_mov_b32_e32 v95, v1
	v_mov_b32_e32 v94, v1
	v_mov_b32_e32 v81, v1
	v_mov_b32_e32 v80, v1
	v_mov_b32_e32 v93, v1
	v_mov_b32_e32 v92, v1
	v_mov_b32_e32 v77, v1
	v_mov_b32_e32 v76, v1
	v_mov_b32_e32 v91, v1
	v_mov_b32_e32 v90, v1
	v_mov_b32_e32 v75, v1
	v_mov_b32_e32 v74, v1
	v_mov_b32_e32 v89, v1
	v_mov_b32_e32 v88, v1
	v_mov_b32_e32 v73, v1
	v_mov_b32_e32 v72, v1
	v_mov_b32_e32 v87, v1
	v_mov_b32_e32 v86, v1
	v_mov_b32_e32 v71, v1
	v_mov_b32_e32 v70, v1
	s_waitcnt vmcnt(43)
	v_lshlrev_b32_e32 v64, 16, v64
	s_waitcnt vmcnt(42)
	v_lshlrev_b32_e32 v127, 16, v106
	s_waitcnt vmcnt(41)
	v_lshlrev_b32_e32 v106, 16, v107
	s_waitcnt vmcnt(40)
	v_lshlrev_b32_e32 v109, 16, v116
	s_waitcnt vmcnt(39)
	v_lshlrev_b32_e32 v108, 16, v117
	v_mov_b32_dpp v78, v106 quad_perm:[1,0,3,2] row_mask:0xf bank_mask:0xf
	v_mov_b32_dpp v99, v109 quad_perm:[1,0,3,2] row_mask:0xf bank_mask:0xf
	s_waitcnt vmcnt(36)
	v_lshlrev_b32_e32 v107, 16, v111
	v_mov_b32_dpp v98, v108 quad_perm:[1,0,3,2] row_mask:0xf bank_mask:0xf
	v_pk_add_f32 v[98:99], v[108:109], v[98:99]
	v_mov_b32_dpp v79, v107 quad_perm:[1,0,3,2] row_mask:0xf bank_mask:0xf
	v_pk_add_f32 v[78:79], v[106:107], v[78:79]
	v_mov_b32_dpp v103, v99 quad_perm:[2,3,0,1] row_mask:0xf bank_mask:0xf
	v_mov_b32_dpp v102, v98 quad_perm:[2,3,0,1] row_mask:0xf bank_mask:0xf
	v_mov_b32_dpp v85, v79 quad_perm:[2,3,0,1] row_mask:0xf bank_mask:0xf
	v_mov_b32_dpp v84, v78 quad_perm:[2,3,0,1] row_mask:0xf bank_mask:0xf
	v_pk_add_f32 v[98:99], v[98:99], v[102:103]
	v_pk_add_f32 v[78:79], v[78:79], v[84:85]
	s_waitcnt vmcnt(35)
	v_lshlrev_b32_e32 v116, 16, v119
	v_mov_b32_dpp v97, v99 row_half_mirror row_mask:0xf bank_mask:0xf
	v_mov_b32_dpp v96, v98 row_half_mirror row_mask:0xf bank_mask:0xf
	v_mov_b32_dpp v83, v79 row_half_mirror row_mask:0xf bank_mask:0xf
	v_mov_b32_dpp v82, v78 row_half_mirror row_mask:0xf bank_mask:0xf
	v_pk_add_f32 v[84:85], v[98:99], v[96:97]
	v_pk_add_f32 v[78:79], v[78:79], v[82:83]
	v_lshlrev_b32_e32 v111, 16, v118
	v_mov_b32_dpp v95, v85 row_mirror row_mask:0xf bank_mask:0xf
	v_mov_b32_dpp v94, v84 row_mirror row_mask:0xf bank_mask:0xf
	v_mov_b32_dpp v81, v79 row_mirror row_mask:0xf bank_mask:0xf
	v_mov_b32_dpp v80, v78 row_mirror row_mask:0xf bank_mask:0xf
	v_pk_add_f32 v[82:83], v[84:85], v[94:95]
	v_pk_add_f32 v[78:79], v[78:79], v[80:81]
	ds_bpermute_b32 v81, v167, v83
	ds_bpermute_b32 v80, v167, v82
	ds_bpermute_b32 v85, v167, v79
	ds_bpermute_b32 v84, v167, v78
	s_waitcnt vmcnt(34)
	v_lshlrev_b32_e32 v112, 16, v112
	s_waitcnt vmcnt(33)
	v_lshlrev_b32_e32 v113, 16, v113
	s_waitcnt lgkmcnt(2)
	v_pk_add_f32 v[80:81], v[82:83], v[80:81]
	ds_bpermute_b32 v83, v168, v81
	s_waitcnt lgkmcnt(1)
	v_pk_add_f32 v[78:79], v[78:79], v[84:85]
	ds_bpermute_b32 v82, v168, v80
	ds_bpermute_b32 v85, v168, v79
	ds_bpermute_b32 v84, v168, v78
	v_lshlrev_b32_e32 v110, 16, v110
	s_waitcnt vmcnt(32)
	v_lshlrev_b32_e32 v114, 16, v114
	s_waitcnt lgkmcnt(2)
	v_pk_add_f32 v[80:81], v[80:81], v[82:83]
	s_waitcnt lgkmcnt(0)
	v_pk_add_f32 v[78:79], v[78:79], v[84:85]
	v_pk_fma_f32 v[80:81], v[80:81], s[42:43], v[108:109] op_sel_hi:[1,0,1] neg_lo:[1,0,0] neg_hi:[1,0,0]
	v_pk_fma_f32 v[78:79], v[78:79], s[42:43], v[106:107] op_sel_hi:[1,0,1] neg_lo:[1,0,0] neg_hi:[1,0,0]
	v_pk_mul_f32 v[82:83], v[80:81], v[80:81]
	v_pk_mul_f32 v[84:85], v[78:79], v[78:79]
	s_nop 0
	v_mov_b32_dpp v93, v83 quad_perm:[1,0,3,2] row_mask:0xf bank_mask:0xf
	v_mov_b32_dpp v92, v82 quad_perm:[1,0,3,2] row_mask:0xf bank_mask:0xf
	v_mov_b32_dpp v77, v85 quad_perm:[1,0,3,2] row_mask:0xf bank_mask:0xf
	v_mov_b32_dpp v76, v84 quad_perm:[1,0,3,2] row_mask:0xf bank_mask:0xf
	v_pk_fma_f32 v[82:83], v[80:81], v[80:81], v[92:93]
	v_pk_fma_f32 v[76:77], v[78:79], v[78:79], v[76:77]
	s_nop 0
	v_mov_b32_dpp v91, v83 quad_perm:[2,3,0,1] row_mask:0xf bank_mask:0xf
	v_mov_b32_dpp v90, v82 quad_perm:[2,3,0,1] row_mask:0xf bank_mask:0xf
	v_mov_b32_dpp v75, v77 quad_perm:[2,3,0,1] row_mask:0xf bank_mask:0xf
	v_mov_b32_dpp v74, v76 quad_perm:[2,3,0,1] row_mask:0xf bank_mask:0xf
	v_pk_add_f32 v[82:83], v[82:83], v[90:91]
	v_pk_add_f32 v[74:75], v[76:77], v[74:75]
	s_nop 0
	v_mov_b32_dpp v89, v83 row_half_mirror row_mask:0xf bank_mask:0xf
	v_mov_b32_dpp v88, v82 row_half_mirror row_mask:0xf bank_mask:0xf
	v_mov_b32_dpp v73, v75 row_half_mirror row_mask:0xf bank_mask:0xf
	v_mov_b32_dpp v72, v74 row_half_mirror row_mask:0xf bank_mask:0xf
	v_pk_add_f32 v[76:77], v[82:83], v[88:89]
	v_pk_add_f32 v[72:73], v[74:75], v[72:73]
	s_nop 0
	v_mov_b32_dpp v87, v77 row_mirror row_mask:0xf bank_mask:0xf
	v_mov_b32_dpp v86, v76 row_mirror row_mask:0xf bank_mask:0xf
	v_mov_b32_dpp v71, v73 row_mirror row_mask:0xf bank_mask:0xf
	v_mov_b32_dpp v70, v72 row_mirror row_mask:0xf bank_mask:0xf
	v_pk_add_f32 v[74:75], v[76:77], v[86:87]
	v_pk_add_f32 v[70:71], v[72:73], v[70:71]
	ds_bpermute_b32 v73, v167, v75
	ds_bpermute_b32 v72, v167, v74
	ds_bpermute_b32 v77, v167, v71
	ds_bpermute_b32 v76, v167, v70
	s_waitcnt lgkmcnt(2)
	v_pk_add_f32 v[72:73], v[74:75], v[72:73]
	ds_bpermute_b32 v75, v168, v73
	s_waitcnt lgkmcnt(1)
	v_pk_add_f32 v[70:71], v[70:71], v[76:77]
	ds_bpermute_b32 v74, v168, v72
	ds_bpermute_b32 v77, v168, v71
	ds_bpermute_b32 v76, v168, v70
	s_waitcnt lgkmcnt(2)
	v_pk_add_f32 v[72:73], v[72:73], v[74:75]
	s_nop 0
	v_pk_fma_f32 v[72:73], v[72:73], s[42:43], v[68:69] op_sel_hi:[1,0,0]
	s_waitcnt lgkmcnt(0)
	v_pk_add_f32 v[70:71], v[70:71], v[76:77]
	v_cmp_gt_f32_e64 s[4:5], s74, v73
	v_pk_fma_f32 v[68:69], v[70:71], s[42:43], v[68:69] op_sel_hi:[1,0,0]
	v_mul_f32_e32 v70, 0x4b800000, v73
	v_mul_f32_e32 v71, 0x4b800000, v72
	v_cmp_gt_f32_e32 vcc, s74, v72
	v_mul_f32_e32 v74, 0x4b800000, v69
	v_mul_f32_e32 v75, 0x4b800000, v68
	v_cmp_gt_f32_e64 s[6:7], s74, v68
	v_cndmask_b32_e64 v70, v73, v70, s[4:5]
	v_cmp_gt_f32_e64 s[8:9], s74, v69
	v_cndmask_b32_e32 v71, v72, v71, vcc
	v_cndmask_b32_e64 v68, v68, v75, s[6:7]
	v_cndmask_b32_e64 v69, v69, v74, s[8:9]
	v_rsq_f32_e32 v70, v70
	v_rsq_f32_e32 v71, v71
	v_rsq_f32_e32 v69, v69
	v_rsq_f32_e32 v68, v68
	v_mul_f32_e32 v72, 0x45800000, v70
	v_mul_f32_e32 v73, 0x45800000, v71
	v_mul_f32_e32 v74, 0x45800000, v69
	v_mul_f32_e32 v75, 0x45800000, v68
	v_cndmask_b32_e64 v70, v70, v72, s[4:5]
	v_cndmask_b32_e32 v71, v71, v73, vcc
	v_cndmask_b32_e64 v69, v69, v74, s[8:9]
	v_cndmask_b32_e64 v68, v68, v75, s[6:7]
	v_mul_f32_e32 v70, v81, v70
	v_mul_f32_e32 v71, v80, v71
	v_mul_f32_e32 v69, v79, v69
	v_mul_f32_e32 v68, v78, v68
	s_waitcnt vmcnt(25)
	v_fmac_f32_e32 v125, v121, v70
	s_waitcnt vmcnt(24)
	v_fmac_f32_e32 v126, v122, v71
	v_fmac_f32_e32 v123, v115, v69
	v_fmac_f32_e32 v124, v120, v68
	v_add_f32_e32 v68, v125, v116
	v_add_f32_e32 v69, v126, v113
	v_add_f32_e32 v64, v123, v64
	v_add_f32_e32 v70, v124, v111
	v_mul_f32_e32 v68, v68, v112
	v_mul_f32_e32 v69, v69, v114
	v_mul_f32_e32 v64, v64, v127
	v_mul_f32_e32 v70, v70, v110
	v_bfe_u32 v71, v68, 16, 1
	v_bfe_u32 v72, v69, 16, 1
	v_bfe_u32 v73, v64, 16, 1
	v_bfe_u32 v74, v70, 16, 1
	v_add3_u32 v68, v68, v71, s78
	v_add3_u32 v69, v69, v72, s78
	v_add3_u32 v64, v64, v73, s78
	v_add3_u32 v70, v70, v74, s78
	global_store_short_d16_hi v[100:101], v68, off offset:256
	global_store_short_d16_hi v[100:101], v69, off offset:384
	global_store_short_d16_hi v[104:105], v64, off offset:2048
	global_store_short_d16_hi v[100:101], v70, off offset:128
	s_branch .Lrwf_loop
